# phase-0 static schedule rebalanced: filter workgroups run only the filter task, the other 240 workgroups share the rest (stride 240)
# baseline (speedup 1.0000x reference)
.LBB0_746:
	v_readlane_b32 s0, v252, 0
	s_cmpk_lt_u32 s0, 0x110
	s_cbranch_scc1 .LBB0_863
	s_addk_i32 s7, 0xf0
	s_add_i32 s4, s4, 1
	s_lshl_b32 s6, s7, 8
	s_sub_i32 s5, 0x6efff, s6
	s_add_i32 s6, s6, 0xfffa1000
	s_cmpk_gt_i32 s7, 0x6ef
	s_cbranch_scc1 .LBB0_863
.LBB0_747:
	s_cmpk_gt_i32 s7, 0x10f
	s_mov_b64 s[0:1], -1
	s_cbranch_scc0 .LBB0_829
	s_cmpk_gt_u32 s7, 0x1cf
	s_cbranch_scc0 .LBB0_814
	s_cmpk_gt_u32 s7, 0x36f
	s_cbranch_scc0 .LBB0_806
	s_cmpk_gt_u32 s7, 0x3ef
	s_cbranch_scc0 .LBB0_803
	s_cmpk_gt_u32 s7, 0x5ef
	s_cbranch_scc0 .LBB0_799
	s_mov_b32 s8, s5
	s_lshl_b32 s0, s7, 8
	s_add_i32 s0, s0, 0xfffa1000
	v_mov_b32_e32 v10, v151
	s_nop 0
	v_add_u32_e32 v2, s0, v10
	v_readlane_b32 s56, v252, 17
	v_readlane_b32 s57, v252, 18
	v_readlane_b32 s58, v252, 19
	v_readlane_b32 s59, v252, 20
	v_readlane_b32 s60, v252, 21
	v_readlane_b32 s61, v252, 22
	v_readlane_b32 s62, v252, 23
	v_readlane_b32 s63, v252, 24
	v_lshlrev_b32_e32 v20, 2, v2
	v_and_b32_e32 v0, 0x1ff, v2
	v_lshrrev_b32_e32 v3, 9, v2
	v_lshl_add_u32 v21, v0, 7, v3
	v_lshlrev_b32_e32 v21, 2, v21
	v_lshl_add_u32 v22, v0, 8, v3
	v_lshlrev_b32_e32 v22, 2, v22
	v_lshlrev_b32_e32 v23, 1, v2
	v_mov_b32_e32 v24, v20
	global_load_dword v32, v24, s[56:57]
	v_add_u32_e32 v24, 0x40000, v24
	global_load_dword v33, v24, s[56:57]
	v_add_u32_e32 v24, 0x40000, v24
	global_load_dword v34, v24, s[56:57]
	v_add_u32_e32 v24, 0x40000, v24
	global_load_dword v35, v24, s[56:57]
	v_add_u32_e32 v24, 0x40000, v24
	global_load_dword v36, v24, s[56:57]
	v_add_u32_e32 v24, 0x40000, v24
	global_load_dword v37, v24, s[56:57]
	v_add_u32_e32 v24, 0x40000, v24
	global_load_dword v38, v24, s[56:57]
	v_add_u32_e32 v24, 0x40000, v24
	global_load_dword v39, v24, s[56:57]
	v_mov_b32_e32 v24, v21
	global_load_dword v40, v24, s[58:59]
	v_add_u32_e32 v24, 0x40000, v24
	global_load_dword v41, v24, s[58:59]
	v_add_u32_e32 v24, 0x40000, v24
	global_load_dword v42, v24, s[58:59]
	v_add_u32_e32 v24, 0x40000, v24
	global_load_dword v43, v24, s[58:59]
	v_add_u32_e32 v24, 0x40000, v24
	global_load_dword v44, v24, s[58:59]
	v_add_u32_e32 v24, 0x40000, v24
	global_load_dword v45, v24, s[58:59]
	v_add_u32_e32 v24, 0x40000, v24
	global_load_dword v46, v24, s[58:59]
	v_add_u32_e32 v24, 0x40000, v24
	global_load_dword v47, v24, s[58:59]
	v_mov_b32_e32 v24, v20
	global_load_dword v48, v24, s[60:61]
	v_add_u32_e32 v24, 0x40000, v24
	global_load_dword v49, v24, s[60:61]
	v_add_u32_e32 v24, 0x40000, v24
	global_load_dword v50, v24, s[60:61]
	v_add_u32_e32 v24, 0x40000, v24
	global_load_dword v51, v24, s[60:61]
	v_add_u32_e32 v24, 0x40000, v24
	global_load_dword v52, v24, s[60:61]
	v_add_u32_e32 v24, 0x40000, v24
	global_load_dword v53, v24, s[60:61]
	v_add_u32_e32 v24, 0x40000, v24
	global_load_dword v54, v24, s[60:61]
	v_add_u32_e32 v24, 0x40000, v24
	global_load_dword v55, v24, s[60:61]
	v_add_u32_e32 v24, 0x40000, v24
	global_load_dword v56, v24, s[60:61]
	v_add_u32_e32 v24, 0x40000, v24
	global_load_dword v57, v24, s[60:61]
	v_add_u32_e32 v24, 0x40000, v24
	global_load_dword v58, v24, s[60:61]
	v_add_u32_e32 v24, 0x40000, v24
	global_load_dword v59, v24, s[60:61]
	v_add_u32_e32 v24, 0x40000, v24
	global_load_dword v60, v24, s[60:61]
	v_add_u32_e32 v24, 0x40000, v24
	global_load_dword v61, v24, s[60:61]
	v_add_u32_e32 v24, 0x40000, v24
	global_load_dword v62, v24, s[60:61]
	v_add_u32_e32 v24, 0x40000, v24
	global_load_dword v63, v24, s[60:61]
	v_mov_b32_e32 v24, v22
	global_load_dword v64, v24, s[62:63]
	global_load_dword v65, v24, s[62:63] offset:512
	v_add_u32_e32 v24, 0x80000, v24
	global_load_dword v66, v24, s[62:63]
	global_load_dword v67, v24, s[62:63] offset:512
	v_add_u32_e32 v24, 0x80000, v24
	global_load_dword v68, v24, s[62:63]
	global_load_dword v69, v24, s[62:63] offset:512
	v_add_u32_e32 v24, 0x80000, v24
	global_load_dword v70, v24, s[62:63]
	global_load_dword v71, v24, s[62:63] offset:512
	v_add_u32_e32 v24, 0x80000, v24
	global_load_dword v72, v24, s[62:63]
	global_load_dword v73, v24, s[62:63] offset:512
	v_add_u32_e32 v24, 0x80000, v24
	global_load_dword v74, v24, s[62:63]
	global_load_dword v75, v24, s[62:63] offset:512
	v_add_u32_e32 v24, 0x80000, v24
	global_load_dword v76, v24, s[62:63]
	global_load_dword v77, v24, s[62:63] offset:512
	v_add_u32_e32 v24, 0x80000, v24
	global_load_dword v78, v24, s[62:63]
	global_load_dword v79, v24, s[62:63] offset:512
	s_waitcnt vmcnt(46)
	v_cvt_pk_bf16_f32 v80, v32, v33
	s_waitcnt vmcnt(44)
	v_cvt_pk_bf16_f32 v81, v34, v35
	s_waitcnt vmcnt(42)
	v_cvt_pk_bf16_f32 v82, v36, v37
	s_waitcnt vmcnt(40)
	v_cvt_pk_bf16_f32 v83, v38, v39
	s_waitcnt vmcnt(38)
	v_cvt_pk_bf16_f32 v84, v40, v41
	s_waitcnt vmcnt(36)
	v_cvt_pk_bf16_f32 v85, v42, v43
	s_waitcnt vmcnt(34)
	v_cvt_pk_bf16_f32 v86, v44, v45
	s_waitcnt vmcnt(32)
	v_cvt_pk_bf16_f32 v87, v46, v47
	s_waitcnt vmcnt(30)
	v_cvt_pk_bf16_f32 v88, v48, v49
	s_waitcnt vmcnt(28)
	v_cvt_pk_bf16_f32 v89, v50, v51
	s_waitcnt vmcnt(26)
	v_cvt_pk_bf16_f32 v90, v52, v53
	s_waitcnt vmcnt(24)
	v_cvt_pk_bf16_f32 v91, v54, v55
	s_waitcnt vmcnt(22)
	v_cvt_pk_bf16_f32 v92, v56, v57
	s_waitcnt vmcnt(20)
	v_cvt_pk_bf16_f32 v93, v58, v59
	s_waitcnt vmcnt(18)
	v_cvt_pk_bf16_f32 v94, v60, v61
	s_waitcnt vmcnt(16)
	v_cvt_pk_bf16_f32 v95, v62, v63
	s_waitcnt vmcnt(14)
	v_cvt_pk_bf16_f32 v96, v64, v65
	s_waitcnt vmcnt(12)
	v_cvt_pk_bf16_f32 v97, v66, v67
	s_waitcnt vmcnt(10)
	v_cvt_pk_bf16_f32 v98, v68, v69
	s_waitcnt vmcnt(8)
	v_cvt_pk_bf16_f32 v99, v70, v71
	s_waitcnt vmcnt(6)
	v_cvt_pk_bf16_f32 v100, v72, v73
	s_waitcnt vmcnt(4)
	v_cvt_pk_bf16_f32 v101, v74, v75
	s_waitcnt vmcnt(2)
	v_cvt_pk_bf16_f32 v102, v76, v77
	s_waitcnt vmcnt(0)
	v_cvt_pk_bf16_f32 v103, v78, v79
	s_add_u32 s10, s94, 0xf500000
	s_addc_u32 s11, s95, 0
	v_mov_b32_e32 v24, v23
	global_store_short v24, v80, s[10:11]
	v_add_u32_e32 v24, 0x20000, v24
	global_store_short_d16_hi v24, v80, s[10:11]
	v_add_u32_e32 v24, 0x20000, v24
	global_store_short v24, v81, s[10:11]
	v_add_u32_e32 v24, 0x20000, v24
	global_store_short_d16_hi v24, v81, s[10:11]
	v_add_u32_e32 v24, 0x20000, v24
	global_store_short v24, v82, s[10:11]
	v_add_u32_e32 v24, 0x20000, v24
	global_store_short_d16_hi v24, v82, s[10:11]
	v_add_u32_e32 v24, 0x20000, v24
	global_store_short v24, v83, s[10:11]
	v_add_u32_e32 v24, 0x20000, v24
	global_store_short_d16_hi v24, v83, s[10:11]
	s_add_u32 s10, s94, 0xf600000
	s_addc_u32 s11, s95, 0
	v_mov_b32_e32 v24, v23
	global_store_short v24, v84, s[10:11]
	v_add_u32_e32 v24, 0x20000, v24
	global_store_short_d16_hi v24, v84, s[10:11]
	v_add_u32_e32 v24, 0x20000, v24
	global_store_short v24, v85, s[10:11]
	v_add_u32_e32 v24, 0x20000, v24
	global_store_short_d16_hi v24, v85, s[10:11]
	v_add_u32_e32 v24, 0x20000, v24
	global_store_short v24, v86, s[10:11]
	v_add_u32_e32 v24, 0x20000, v24
	global_store_short_d16_hi v24, v86, s[10:11]
	v_add_u32_e32 v24, 0x20000, v24
	global_store_short v24, v87, s[10:11]
	v_add_u32_e32 v24, 0x20000, v24
	global_store_short_d16_hi v24, v87, s[10:11]
	s_add_u32 s10, s94, 0xf700000
	s_addc_u32 s11, s95, 0
	v_mov_b32_e32 v24, v23
	global_store_short v24, v88, s[10:11]
	v_add_u32_e32 v24, 0x20000, v24
	global_store_short_d16_hi v24, v88, s[10:11]
	v_add_u32_e32 v24, 0x20000, v24
	global_store_short v24, v89, s[10:11]
	v_add_u32_e32 v24, 0x20000, v24
	global_store_short_d16_hi v24, v89, s[10:11]
	v_add_u32_e32 v24, 0x20000, v24
	global_store_short v24, v90, s[10:11]
	v_add_u32_e32 v24, 0x20000, v24
	global_store_short_d16_hi v24, v90, s[10:11]
	v_add_u32_e32 v24, 0x20000, v24
	global_store_short v24, v91, s[10:11]
	v_add_u32_e32 v24, 0x20000, v24
	global_store_short_d16_hi v24, v91, s[10:11]
	v_add_u32_e32 v24, 0x20000, v24
	global_store_short v24, v92, s[10:11]
	v_add_u32_e32 v24, 0x20000, v24
	global_store_short_d16_hi v24, v92, s[10:11]
	v_add_u32_e32 v24, 0x20000, v24
	global_store_short v24, v93, s[10:11]
	v_add_u32_e32 v24, 0x20000, v24
	global_store_short_d16_hi v24, v93, s[10:11]
	v_add_u32_e32 v24, 0x20000, v24
	global_store_short v24, v94, s[10:11]
	v_add_u32_e32 v24, 0x20000, v24
	global_store_short_d16_hi v24, v94, s[10:11]
	v_add_u32_e32 v24, 0x20000, v24
	global_store_short v24, v95, s[10:11]
	v_add_u32_e32 v24, 0x20000, v24
	global_store_short_d16_hi v24, v95, s[10:11]
	s_add_u32 s10, s94, 0xf900000
	s_addc_u32 s11, s95, 0
	v_mov_b32_e32 v24, v23
	global_store_short v24, v96, s[10:11]
	v_add_u32_e32 v24, 0x20000, v24
	global_store_short_d16_hi v24, v96, s[10:11]
	v_add_u32_e32 v24, 0x20000, v24
	global_store_short v24, v97, s[10:11]
	v_add_u32_e32 v24, 0x20000, v24
	global_store_short_d16_hi v24, v97, s[10:11]
	v_add_u32_e32 v24, 0x20000, v24
	global_store_short v24, v98, s[10:11]
	v_add_u32_e32 v24, 0x20000, v24
	global_store_short_d16_hi v24, v98, s[10:11]
	v_add_u32_e32 v24, 0x20000, v24
	global_store_short v24, v99, s[10:11]
	v_add_u32_e32 v24, 0x20000, v24
	global_store_short_d16_hi v24, v99, s[10:11]
	v_add_u32_e32 v24, 0x20000, v24
	global_store_short v24, v100, s[10:11]
	v_add_u32_e32 v24, 0x20000, v24
	global_store_short_d16_hi v24, v100, s[10:11]
	v_add_u32_e32 v24, 0x20000, v24
	global_store_short v24, v101, s[10:11]
	v_add_u32_e32 v24, 0x20000, v24
	global_store_short_d16_hi v24, v101, s[10:11]
	v_add_u32_e32 v24, 0x20000, v24
	global_store_short v24, v102, s[10:11]
	v_add_u32_e32 v24, 0x20000, v24
	global_store_short_d16_hi v24, v102, s[10:11]
	v_add_u32_e32 v24, 0x20000, v24
	global_store_short v24, v103, s[10:11]
	v_add_u32_e32 v24, 0x20000, v24
	global_store_short_d16_hi v24, v103, s[10:11]
	s_mov_b64 s[0:1], exec
	s_branch .LBB0_768
	s_mov_b32 s0, 0x80000
	v_cmp_gt_i32_e32 vcc, s0, v2
	s_and_saveexec_b64 s[0:1], vcc
	s_cbranch_execz .LBB0_760
	v_max_i32_e32 v0, 0x70000, v2
	v_add_u32_e32 v0, s8, v0
	v_sub_u32_e32 v6, v0, v10
	s_mov_b32 s9, 0xffff
	v_cmp_lt_u32_e32 vcc, s9, v6
	s_mov_b64 s[38:39], -1
	v_mov_b32_e32 v4, v2
	s_and_saveexec_b64 s[28:29], vcc
	s_cbranch_execz .LBB0_757
	v_add_u32_e32 v0, s6, v10
	v_max_i32_e32 v0, 0x70000, v0
	v_add_u32_e32 v0, s5, v0
	v_sub_u32_e32 v0, v0, v10
	v_add_u32_e32 v3, 0x10000, v2
	v_add_u32_sdwa v0, v0, v180 dst_sel:DWORD dst_unused:UNUSED_PAD src0_sel:WORD_1 src1_sel:DWORD
	v_readlane_b32 s52, v252, 13
	v_readlane_b32 s10, v253, 12
	v_readlane_b32 s12, v253, 14
	v_and_b32_e32 v7, 0x1fffe, v0
	s_mov_b64 s[38:39], 0
	v_mov_b64_e32 v[4:5], v[2:3]
	v_readlane_b32 s56, v252, 17
	v_readlane_b32 s57, v252, 18
	v_readlane_b32 s58, v252, 19
	v_readlane_b32 s59, v252, 20
	v_readlane_b32 s11, v253, 13
	v_readlane_b32 s13, v253, 15
	v_readlane_b32 s53, v252, 14
	v_readlane_b32 s54, v252, 15
	v_readlane_b32 s55, v252, 16
	v_readlane_b32 s60, v252, 21
	v_readlane_b32 s61, v252, 22
	v_readlane_b32 s62, v252, 23
	v_readlane_b32 s63, v252, 24
	v_readlane_b32 s64, v252, 25
	v_readlane_b32 s65, v252, 26
	v_readlane_b32 s66, v252, 27
	v_readlane_b32 s67, v252, 28
